# norm2 (k=7) and norm1 (in ffn-out phase) rows: all 16 loads issued at once instead of 8 dependent round trips
# speedup vs baseline: 1.0160x; 1.0160x over previous
.LBB0_155:
	v_mov_b32_e32 v0, v1
	s_cmpk_gt_i32 s46, 0x1ff
	v_mbcnt_lo_u32_b32 v0, -1, v0
	v_mbcnt_hi_u32_b32 v0, -1, v0
	s_waitcnt vmcnt(0)
	v_add_u32_e32 v108, s80, v0
	s_mov_b64 s[20:21], -1
	v_lshlrev_b32_e32 v109, 2, v108
	s_cbranch_scc0 .LBB0_157
	s_lshl_b32 s20, s46, 2
	v_ashrrev_i32_e32 v0, 6, v108
	s_add_i32 s24, s20, 0xfffff800
	s_load_dwordx2 s[20:21], s[36:37], 0x0
	v_add_u32_e32 v26, s24, v0
	v_ashrrev_i32_e32 v27, 31, v26
	s_waitcnt lgkmcnt(0)
	v_lshl_add_u64 v[2:3], v[26:27], 0, s[94:95]
	v_lshlrev_b64 v[2:3], 12, v[2:3]
	v_and_b32_e32 v52, 0xfc, v109
	s_waitcnt lgkmcnt(0)
	v_lshl_add_u64 v[2:3], s[20:21], 0, v[2:3]
	v_lshlrev_b32_e32 v0, 2, v52
	v_lshl_add_u64 v[2:3], v[2:3], 0, v[0:1]
	global_load_dwordx4 v[66:69], v[2:3], off
	global_load_dwordx4 v[70:73], v[2:3], off offset:1024
	global_load_dwordx4 v[74:77], v[2:3], off offset:2048
	global_load_dwordx4 v[78:81], v[2:3], off offset:3072
	s_mov_b64 s[20:21], s[12:13]
	v_readlane_b32 s12, v254, 60
	v_readlane_b32 s13, v254, 61
	v_ashrrev_i32_e32 v20, 12, v26
	v_add_u32_e32 v20, 1, v20
	v_mov_b64_e32 v[18:19], s[12:13]
	s_mov_b64 s[12:13], s[20:21]
	v_cndmask_b32_e64 v20, 0, v20, s[12:13]
	v_add_u32_e32 v20, s31, v20
	s_movk_i32 s20, 0x6000
	v_mad_i64_i32 v[18:19], s[20:21], v20, s20, v[18:19]
	v_lshl_add_u64 v[30:31], v[18:19], 0, s[8:9]
	v_lshl_add_u64 v[62:63], v[30:31], 0, v[0:1]
	v_lshl_add_u64 v[60:61], v[18:19], 0, v[0:1]
	global_load_dwordx4 v[82:85], v0, s[4:5]
	global_load_dwordx4 v[86:89], v0, s[4:5] offset:1024
	global_load_dwordx4 v[90:93], v0, s[4:5] offset:2048
	global_load_dwordx4 v[94:97], v0, s[4:5] offset:3072
	global_load_dwordx4 v[98:101], v[60:61], off
	global_load_dwordx4 v[102:105], v[60:61], off offset:1024
	global_load_dwordx4 v[106:109], v[60:61], off offset:2048
	global_load_dwordx4 v[110:113], v[60:61], off offset:3072
	global_load_dwordx4 v[114:117], v[62:63], off
	global_load_dwordx4 v[118:121], v[62:63], off offset:1024
	global_load_dwordx4 v[122:125], v[62:63], off offset:2048
	global_load_dwordx4 v[126:129], v[62:63], off offset:3072
	v_readlane_b32 s20, v252, 20
	v_readlane_b32 s21, v252, 21
	v_lshlrev_b64 v[26:27], 11, v[26:27]
	s_nop 1
	v_lshl_add_u64 v[26:27], s[20:21], 0, v[26:27]
	v_lshlrev_b32_e32 v36, 1, v52
	v_mov_b32_e32 v37, v1
	v_lshl_add_u64 v[26:27], v[26:27], 0, v[36:37]
	v_cmp_lt_i32_e32 vcc, v199, v221
	s_nop 1
	v_cndmask_b32_e32 v36, v220, v199, vcc
	v_lshlrev_b32_e32 v132, 2, v36
	v_cmp_lt_i32_e32 vcc, v200, v221
	s_nop 1
	v_cndmask_b32_e32 v36, v220, v200, vcc
	v_lshlrev_b32_e32 v133, 2, v36
	v_cmp_lt_i32_e32 vcc, v201, v221
	s_nop 1
	v_cndmask_b32_e32 v36, v220, v201, vcc
	v_lshlrev_b32_e32 v134, 2, v36
	v_cmp_lt_i32_e32 vcc, v235, v221
	s_nop 1
	v_cndmask_b32_e32 v36, v220, v235, vcc
	v_lshlrev_b32_e32 v135, 2, v36
	v_cmp_lt_i32_e32 vcc, v226, v221
	s_nop 1
	v_cndmask_b32_e32 v36, v220, v226, vcc
	v_lshlrev_b32_e32 v136, 2, v36
	v_cmp_lt_i32_e32 vcc, v227, v221
	s_nop 1
	v_cndmask_b32_e32 v36, v220, v227, vcc
	v_lshlrev_b32_e32 v137, 2, v36
	s_waitcnt vmcnt(12)
	v_pk_mul_f32 v[130:131], v[66:67], v[66:67]
	v_pk_fma_f32 v[130:131], v[68:69], v[68:69], v[130:131]
	v_pk_fma_f32 v[130:131], v[70:71], v[70:71], v[130:131]
	v_pk_fma_f32 v[130:131], v[72:73], v[72:73], v[130:131]
	v_pk_fma_f32 v[130:131], v[74:75], v[74:75], v[130:131]
	v_pk_fma_f32 v[130:131], v[76:77], v[76:77], v[130:131]
	v_pk_fma_f32 v[130:131], v[78:79], v[78:79], v[130:131]
	v_pk_fma_f32 v[130:131], v[80:81], v[80:81], v[130:131]
	s_nop 0
	v_add_f32_e32 v44, v130, v131
	ds_bpermute_b32 v45, v132, v44
	s_waitcnt lgkmcnt(0)
	v_add_f32_e32 v44, v44, v45
	ds_bpermute_b32 v45, v133, v44
	s_waitcnt lgkmcnt(0)
	v_add_f32_e32 v44, v44, v45
	ds_bpermute_b32 v45, v134, v44
	s_waitcnt lgkmcnt(0)
	v_add_f32_e32 v44, v44, v45
	ds_bpermute_b32 v45, v135, v44
	s_waitcnt lgkmcnt(0)
	v_add_f32_e32 v44, v44, v45
	ds_bpermute_b32 v45, v136, v44
	s_waitcnt lgkmcnt(0)
	v_add_f32_e32 v44, v44, v45
	ds_bpermute_b32 v45, v137, v44
	s_waitcnt lgkmcnt(0)
	v_add_f32_e32 v44, v44, v45
	v_fmamk_f32 v44, v44, 0x3a800000, v187
	v_cmp_gt_f32_e32 vcc, s82, v44
	v_mul_f32_e32 v45, 0x4b800000, v44
	s_nop 0
	v_cndmask_b32_e32 v44, v44, v45, vcc
	v_rsq_f32_e32 v44, v44
	s_nop 0
	v_mul_f32_e32 v45, 0x45800000, v44
	v_cndmask_b32_e32 v44, v44, v45, vcc
	s_waitcnt vmcnt(0)
	v_pk_mul_f32 v[66:67], v[66:67], v[44:45] op_sel_hi:[1,0]
	v_pk_mul_f32 v[68:69], v[68:69], v[44:45] op_sel_hi:[1,0]
	v_pk_add_f32 v[114:115], v[114:115], 1.0 op_sel_hi:[1,0]
	v_pk_add_f32 v[116:117], v[116:117], 1.0 op_sel_hi:[1,0]
	v_pk_mul_f32 v[66:67], v[82:83], v[66:67]
	v_pk_mul_f32 v[68:69], v[84:85], v[68:69]
	v_pk_fma_f32 v[98:99], v[114:115], v[66:67], v[98:99]
	v_pk_fma_f32 v[100:101], v[68:69], v[116:117], v[100:101]
	s_nop 0
	v_cvt_pk_bf16_f32 v98, v98, v99
	v_cvt_pk_bf16_f32 v99, v100, v101
	global_store_dwordx2 v[26:27], v[98:99], off
	v_pk_mul_f32 v[70:71], v[70:71], v[44:45] op_sel_hi:[1,0]
	v_pk_mul_f32 v[72:73], v[72:73], v[44:45] op_sel_hi:[1,0]
	v_pk_add_f32 v[118:119], v[118:119], 1.0 op_sel_hi:[1,0]
	v_pk_add_f32 v[120:121], v[120:121], 1.0 op_sel_hi:[1,0]
	v_pk_mul_f32 v[70:71], v[86:87], v[70:71]
	v_pk_mul_f32 v[72:73], v[88:89], v[72:73]
	v_pk_fma_f32 v[102:103], v[118:119], v[70:71], v[102:103]
	v_pk_fma_f32 v[104:105], v[72:73], v[120:121], v[104:105]
	s_nop 0
	v_cvt_pk_bf16_f32 v102, v102, v103
	v_cvt_pk_bf16_f32 v103, v104, v105
	global_store_dwordx2 v[26:27], v[102:103], off offset:512
	v_pk_mul_f32 v[74:75], v[74:75], v[44:45] op_sel_hi:[1,0]
	v_pk_mul_f32 v[76:77], v[76:77], v[44:45] op_sel_hi:[1,0]
	v_pk_add_f32 v[122:123], v[122:123], 1.0 op_sel_hi:[1,0]
	v_pk_add_f32 v[124:125], v[124:125], 1.0 op_sel_hi:[1,0]
	v_pk_mul_f32 v[74:75], v[90:91], v[74:75]
	v_pk_mul_f32 v[76:77], v[92:93], v[76:77]
	v_pk_fma_f32 v[106:107], v[122:123], v[74:75], v[106:107]
	v_pk_fma_f32 v[108:109], v[76:77], v[124:125], v[108:109]
	s_nop 0
	v_cvt_pk_bf16_f32 v106, v106, v107
	v_cvt_pk_bf16_f32 v107, v108, v109
	global_store_dwordx2 v[26:27], v[106:107], off offset:1024
	v_pk_mul_f32 v[78:79], v[78:79], v[44:45] op_sel_hi:[1,0]
	v_pk_mul_f32 v[80:81], v[80:81], v[44:45] op_sel_hi:[1,0]
	v_pk_add_f32 v[126:127], v[126:127], 1.0 op_sel_hi:[1,0]
	v_pk_add_f32 v[128:129], v[128:129], 1.0 op_sel_hi:[1,0]
	v_pk_mul_f32 v[78:79], v[94:95], v[78:79]
	v_pk_mul_f32 v[80:81], v[96:97], v[80:81]
	v_pk_fma_f32 v[110:111], v[126:127], v[78:79], v[110:111]
	v_pk_fma_f32 v[112:113], v[80:81], v[128:129], v[112:113]
	s_nop 0
	v_cvt_pk_bf16_f32 v110, v110, v111
	v_cvt_pk_bf16_f32 v111, v112, v113
	global_store_dwordx2 v[26:27], v[110:111], off offset:1536
	s_mov_b64 s[20:21], 0

.LBB0_198:
	v_mov_b32_e32 v0, v1
	v_readlane_b32 s22, v255, 2
	v_mbcnt_lo_u32_b32 v0, -1, v0
	v_mbcnt_hi_u32_b32 v0, -1, v0
	v_add_u32_e32 v0, s80, v0
	s_mul_i32 s22, s22, 3
	s_waitcnt lgkmcnt(0)
	v_ashrrev_i32_e32 v2, 6, v0
	v_add_u32_e32 v2, s20, v2
	v_ashrrev_i32_e32 v3, 31, v2
	v_lshl_add_u64 v[4:5], v[2:3], 0, s[94:95]
	v_ashrrev_i32_e32 v6, 12, v2
	v_lshlrev_b32_e32 v0, 2, v0
	v_lshlrev_b64 v[4:5], 12, v[4:5]
	v_add_u32_e32 v6, 1, v6
	v_and_b32_e32 v24, 0xfc, v0
	v_lshl_add_u64 v[4:5], s[64:65], 0, v[4:5]
	v_cndmask_b32_e64 v6, v6, 0, s[12:13]
	v_lshlrev_b32_e32 v0, 2, v24
	v_readlane_b32 s23, v255, 3
	v_add_u32_e32 v6, s22, v6
	v_lshl_add_u64 v[18:19], v[4:5], 0, v[0:1]
	v_mov_b64_e32 v[4:5], s[66:67]
	v_cmp_lt_i32_e32 vcc, v199, v221
	v_mad_i64_i32 v[4:5], s[22:23], v6, s25, v[4:5]
	s_nop 0
	v_cndmask_b32_e32 v6, v220, v199, vcc
	v_cmp_lt_i32_e32 vcc, v200, v221
	v_lshlrev_b32_e32 v54, 2, v6
	s_mov_b64 s[22:23], 0x4b03000
	v_cndmask_b32_e32 v6, v220, v200, vcc
	v_cmp_lt_i32_e32 vcc, v201, v221
	v_lshlrev_b32_e32 v55, 2, v6
	v_lshl_add_u64 v[20:21], v[4:5], 0, s[22:23]
	v_cndmask_b32_e32 v6, v220, v201, vcc
	v_cmp_lt_i32_e32 vcc, v235, v221
	v_lshlrev_b32_e32 v56, 2, v6
	s_mov_b64 s[22:23], 0x4b04000
	v_cndmask_b32_e32 v6, v220, v235, vcc
	v_cmp_lt_i32_e32 vcc, v226, v221
	v_lshlrev_b32_e32 v57, 2, v6
	v_lshlrev_b64 v[2:3], 11, v[2:3]
	v_cndmask_b32_e32 v6, v220, v226, vcc
	v_cmp_lt_i32_e32 vcc, v227, v221
	v_lshl_add_u64 v[38:39], v[4:5], 0, s[22:23]
	v_lshlrev_b32_e32 v58, 2, v6
	v_cndmask_b32_e32 v6, v220, v227, vcc
	v_lshl_add_u64 v[22:23], s[72:73], 0, v[2:3]
	v_lshl_add_u64 v[2:3], v[20:21], 0, v[0:1]
	v_lshl_add_u64 v[14:15], v[38:39], 0, v[0:1]
	v_lshlrev_b32_e32 v59, 2, v6
	v_mov_b32_e32 v60, v2
	v_mov_b32_e32 v61, v3
	v_mov_b32_e32 v62, v14
	v_mov_b32_e32 v63, v15
	global_load_dwordx4 v[66:69], v[18:19], off
	global_load_dwordx4 v[70:73], v[18:19], off offset:1024
	global_load_dwordx4 v[74:77], v[18:19], off offset:2048
	global_load_dwordx4 v[78:81], v[18:19], off offset:3072
	global_load_dwordx4 v[82:85], v0, s[4:5]
	global_load_dwordx4 v[86:89], v0, s[4:5] offset:1024
	global_load_dwordx4 v[90:93], v0, s[4:5] offset:2048
	global_load_dwordx4 v[94:97], v0, s[4:5] offset:3072
	global_load_dwordx4 v[98:101], v[60:61], off
	global_load_dwordx4 v[102:105], v[60:61], off offset:1024
	global_load_dwordx4 v[106:109], v[60:61], off offset:2048
	global_load_dwordx4 v[110:113], v[60:61], off offset:3072
	global_load_dwordx4 v[114:117], v[62:63], off
	global_load_dwordx4 v[118:121], v[62:63], off offset:1024
	global_load_dwordx4 v[122:125], v[62:63], off offset:2048
	global_load_dwordx4 v[126:129], v[62:63], off offset:3072
	v_lshlrev_b32_e32 v14, 1, v24
	v_mov_b32_e32 v15, v1
	v_lshl_add_u64 v[26:27], v[22:23], 0, v[14:15]
	s_add_i32 s21, s21, s81
	s_add_i32 s20, s20, s24
	v_readlane_b32 s22, v255, 2
	v_readlane_b32 s23, v255, 3
	s_cmpk_gt_i32 s21, 0x7ff
	s_waitcnt vmcnt(12)
	v_pk_mul_f32 v[130:131], v[66:67], v[66:67]
	v_pk_fma_f32 v[130:131], v[68:69], v[68:69], v[130:131]
	v_pk_fma_f32 v[130:131], v[70:71], v[70:71], v[130:131]
	v_pk_fma_f32 v[130:131], v[72:73], v[72:73], v[130:131]
	v_pk_fma_f32 v[130:131], v[74:75], v[74:75], v[130:131]
	v_pk_fma_f32 v[130:131], v[76:77], v[76:77], v[130:131]
	v_pk_fma_f32 v[130:131], v[78:79], v[78:79], v[130:131]
	v_pk_fma_f32 v[130:131], v[80:81], v[80:81], v[130:131]
	s_nop 0
	v_add_f32_e32 v44, v130, v131
	ds_bpermute_b32 v45, v54, v44
	s_waitcnt lgkmcnt(0)
	v_add_f32_e32 v44, v44, v45
	ds_bpermute_b32 v45, v55, v44
	s_waitcnt lgkmcnt(0)
	v_add_f32_e32 v44, v44, v45
	ds_bpermute_b32 v45, v56, v44
	s_waitcnt lgkmcnt(0)
	v_add_f32_e32 v44, v44, v45
	ds_bpermute_b32 v45, v57, v44
	s_waitcnt lgkmcnt(0)
	v_add_f32_e32 v44, v44, v45
	ds_bpermute_b32 v45, v58, v44
	s_waitcnt lgkmcnt(0)
	v_add_f32_e32 v44, v44, v45
	ds_bpermute_b32 v45, v59, v44
	s_waitcnt lgkmcnt(0)
	v_add_f32_e32 v44, v44, v45
	v_fmamk_f32 v44, v44, 0x3a800000, v187
	v_cmp_gt_f32_e32 vcc, s82, v44
	v_mul_f32_e32 v45, 0x4b800000, v44
	s_nop 0
	v_cndmask_b32_e32 v44, v44, v45, vcc
	v_rsq_f32_e32 v44, v44
	s_nop 0
	v_mul_f32_e32 v45, 0x45800000, v44
	v_cndmask_b32_e32 v44, v44, v45, vcc
	s_waitcnt vmcnt(0)
	v_pk_mul_f32 v[66:67], v[66:67], v[44:45] op_sel_hi:[1,0]
	v_pk_mul_f32 v[68:69], v[68:69], v[44:45] op_sel_hi:[1,0]
	v_pk_add_f32 v[114:115], v[114:115], 1.0 op_sel_hi:[1,0]
	v_pk_add_f32 v[116:117], v[116:117], 1.0 op_sel_hi:[1,0]
	v_pk_mul_f32 v[66:67], v[82:83], v[66:67]
	v_pk_mul_f32 v[68:69], v[84:85], v[68:69]
	v_pk_fma_f32 v[98:99], v[114:115], v[66:67], v[98:99]
	v_pk_fma_f32 v[100:101], v[68:69], v[116:117], v[100:101]
	s_nop 0
	v_cvt_pk_bf16_f32 v98, v98, v99
	v_cvt_pk_bf16_f32 v99, v100, v101
	global_store_dwordx2 v[26:27], v[98:99], off
	v_pk_mul_f32 v[70:71], v[70:71], v[44:45] op_sel_hi:[1,0]
	v_pk_mul_f32 v[72:73], v[72:73], v[44:45] op_sel_hi:[1,0]
	v_pk_add_f32 v[118:119], v[118:119], 1.0 op_sel_hi:[1,0]
	v_pk_add_f32 v[120:121], v[120:121], 1.0 op_sel_hi:[1,0]
	v_pk_mul_f32 v[70:71], v[86:87], v[70:71]
	v_pk_mul_f32 v[72:73], v[88:89], v[72:73]
	v_pk_fma_f32 v[102:103], v[118:119], v[70:71], v[102:103]
	v_pk_fma_f32 v[104:105], v[72:73], v[120:121], v[104:105]
	s_nop 0
	v_cvt_pk_bf16_f32 v102, v102, v103
	v_cvt_pk_bf16_f32 v103, v104, v105
	global_store_dwordx2 v[26:27], v[102:103], off offset:512
	v_pk_mul_f32 v[74:75], v[74:75], v[44:45] op_sel_hi:[1,0]
	v_pk_mul_f32 v[76:77], v[76:77], v[44:45] op_sel_hi:[1,0]
	v_pk_add_f32 v[122:123], v[122:123], 1.0 op_sel_hi:[1,0]
	v_pk_add_f32 v[124:125], v[124:125], 1.0 op_sel_hi:[1,0]
	v_pk_mul_f32 v[74:75], v[90:91], v[74:75]
	v_pk_mul_f32 v[76:77], v[92:93], v[76:77]
	v_pk_fma_f32 v[106:107], v[122:123], v[74:75], v[106:107]
	v_pk_fma_f32 v[108:109], v[76:77], v[124:125], v[108:109]
	s_nop 0
	v_cvt_pk_bf16_f32 v106, v106, v107
	v_cvt_pk_bf16_f32 v107, v108, v109
	global_store_dwordx2 v[26:27], v[106:107], off offset:1024
	v_pk_mul_f32 v[78:79], v[78:79], v[44:45] op_sel_hi:[1,0]
	v_pk_mul_f32 v[80:81], v[80:81], v[44:45] op_sel_hi:[1,0]
	v_pk_add_f32 v[126:127], v[126:127], 1.0 op_sel_hi:[1,0]
	v_pk_add_f32 v[128:129], v[128:129], 1.0 op_sel_hi:[1,0]
	v_pk_mul_f32 v[78:79], v[94:95], v[78:79]
	v_pk_mul_f32 v[80:81], v[96:97], v[80:81]
	v_pk_fma_f32 v[110:111], v[126:127], v[78:79], v[110:111]
	v_pk_fma_f32 v[112:113], v[80:81], v[128:129], v[112:113]
	s_nop 0
	v_cvt_pk_bf16_f32 v110, v110, v111
	v_cvt_pk_bf16_f32 v111, v112, v113
	global_store_dwordx2 v[26:27], v[110:111], off offset:1536
	s_cbranch_scc0 .LBB0_198
	s_mov_b32 s76, 0x8000
	s_mov_b32 s75, 0x60000
